# expert-table quantisation filler: both rows of a pair loaded together (one HBM round trip per pair)
# baseline (speedup 1.0000x reference)
.LBB0_278:
	global_load_dwordx4 v[18:21], v[36:37], off offset:16
	global_load_dwordx4 v[22:25], v[36:37], off
	global_load_dwordx4 v[26:29], v[36:37], off offset:-16
	global_load_dwordx4 v[30:33], v[36:37], off offset:-32
	v_cmp_gt_i32_e32 vcc, s16, v43
	v_add_u32_e32 v2, 1, v43
	v_cmp_gt_i32_e64 s[2:3], s16, v2
	s_nop 1
	v_cndmask_b32_e64 v2, v43, v2, s[2:3]
	v_ashrrev_i32_e32 v3, 31, v2
	v_lshlrev_b64 v[2:3], 12, v[2:3]
	v_lshl_add_u64 v[14:15], v[34:35], 0, v[2:3]
	global_load_dwordx4 v[2:5], v[14:15], off offset:48
	global_load_dwordx4 v[6:9], v[14:15], off offset:32
	global_load_dwordx4 v[10:13], v[14:15], off offset:16
	s_nop 0
	global_load_dwordx4 v[14:17], v[14:15], off
	s_waitcnt vmcnt(7)
	v_max_f32_e64 v62, |v20|, |v20|
	s_waitcnt vmcnt(5)
	v_max_f32_e64 v61, |v28|, |v28|
	s_waitcnt vmcnt(4)
	v_max_f32_e64 v0, |v33|, |v33|
	v_max_f32_e64 v60, |v32|, |v32|
	v_max_f32_e32 v0, v60, v0
	v_max_f32_e64 v60, |v29|, |v29|
	v_max_f32_e32 v60, v61, v60
	v_max3_f32 v0, |v30|, |v31|, v0
	v_max3_f32 v60, |v26|, |v27|, v60
	v_max3_f32 v0, v0, 0, v60
	v_max_f32_e64 v60, |v25|, |v25|
	v_max_f32_e64 v61, |v24|, |v24|
	v_max_f32_e32 v60, v61, v60
	v_max_f32_e64 v61, |v21|, |v21|
	v_max_f32_e32 v61, v62, v61
	v_max3_f32 v60, |v22|, |v23|, v60
	v_max3_f32 v61, |v18|, |v19|, v61
	v_max3_f32 v0, v0, v60, v61
	s_waitcnt vmcnt(3)
	v_max_f32_e64 v54, |v4|, |v4|
	s_waitcnt vmcnt(1)
	v_max_f32_e64 v53, |v12|, |v12|
	s_waitcnt vmcnt(0) lgkmcnt(0)
	v_max_f32_e64 v51, |v17|, |v17|
	v_max_f32_e64 v52, |v16|, |v16|
	v_max_f32_e32 v51, v52, v51
	v_max_f32_e64 v52, |v13|, |v13|
	v_max_f32_e32 v52, v53, v52
	v_max3_f32 v51, |v14|, |v15|, v51
	v_max3_f32 v52, |v10|, |v11|, v52
	v_max3_f32 v51, v51, 0, v52
	v_max_f32_e64 v52, |v9|, |v9|
	v_max_f32_e64 v53, |v8|, |v8|
	v_max_f32_e32 v52, v53, v52
	v_max_f32_e64 v53, |v5|, |v5|
	v_max_f32_e32 v53, v54, v53
	v_max3_f32 v52, |v6|, |v7|, v52
	v_max3_f32 v53, |v2|, |v3|, v53
	v_max3_f32 v51, v51, v52, v53
	ds_bpermute_b32 v52, v44, v0
	v_cndmask_b32_e64 v54, 0, 1, s[8:9]
	v_cmp_ne_u32_e64 s[4:5], 1, v54
	s_waitcnt lgkmcnt(0)
	v_max_f32_e32 v52, v52, v52
	v_max_f32_e32 v0, v0, v52
	ds_bpermute_b32 v52, v45, v0
	s_waitcnt lgkmcnt(0)
	v_max_f32_e32 v52, v52, v52
	v_max_f32_e32 v0, v0, v52
	ds_bpermute_b32 v52, v46, v0
	s_waitcnt lgkmcnt(0)
	v_max_f32_e32 v52, v52, v52
	v_max_f32_e32 v0, v0, v52
	ds_bpermute_b32 v52, v47, v0
	s_waitcnt lgkmcnt(0)
	v_max_f32_e32 v52, v52, v52
	v_max_f32_e32 v0, v0, v52
	ds_bpermute_b32 v52, v48, v0
	s_waitcnt lgkmcnt(0)
	v_max_f32_e32 v52, v52, v52
	v_max_f32_e32 v52, v0, v52
	ds_bpermute_b32 v0, v44, v51
	ds_bpermute_b32 v53, v49, v52
	s_waitcnt lgkmcnt(1)
	v_max_f32_e32 v0, v0, v0
	v_max_f32_e32 v0, v51, v0
	ds_bpermute_b32 v51, v45, v0
	s_waitcnt lgkmcnt(0)
	v_max_f32_e32 v51, v51, v51
	v_max_f32_e32 v0, v0, v51
	ds_bpermute_b32 v51, v46, v0
	s_waitcnt lgkmcnt(0)
	v_max_f32_e32 v51, v51, v51
	v_max_f32_e32 v0, v0, v51
	ds_bpermute_b32 v51, v47, v0
	s_waitcnt lgkmcnt(0)
	v_max_f32_e32 v51, v51, v51
	v_max_f32_e32 v0, v0, v51
	ds_bpermute_b32 v51, v48, v0
	s_waitcnt lgkmcnt(0)
	v_max_f32_e32 v51, v51, v51
	v_max_f32_e32 v0, v0, v51
	ds_bpermute_b32 v51, v49, v0
	s_and_saveexec_b64 s[12:13], vcc
	s_cbranch_execz .LBB0_283
	v_max_f32_e32 v53, v53, v53
	v_max_f32_e32 v52, v52, v52
	v_max_f32_e32 v52, v52, v53
	v_div_scale_f32 v53, s[14:15], v52, v52, v42
	v_rcp_f32_e32 v54, v53
	s_mov_b64 s[14:15], -1
	v_fma_f32 v55, -v53, v54, 1.0
	v_fmac_f32_e32 v54, v55, v54
	v_div_scale_f32 v55, vcc, v42, v52, v42
	v_mul_f32_e32 v56, v55, v54
	v_fma_f32 v57, -v53, v56, v55
	v_fmac_f32_e32 v56, v57, v54
	v_fma_f32 v53, -v53, v56, v55
	v_div_fmas_f32 v53, v53, v54, v56
	v_div_fixup_f32 v53, v53, v52, v42
	v_cmp_lt_f32_e32 vcc, 0, v52
	s_nop 1
	v_cndmask_b32_e32 v56, 0, v53, vcc
	v_mul_f32_e32 v55, v30, v56
	s_and_b64 vcc, exec, s[4:5]
	v_mul_f32_e32 v54, v31, v56
	v_mul_f32_e32 v53, v32, v56
	v_mul_f32_e32 v33, v33, v56
	v_mul_f32_e32 v32, v26, v56
	v_mul_f32_e32 v31, v27, v56
	v_mul_f32_e32 v30, v28, v56
	v_mul_f32_e32 v29, v29, v56
	v_mul_f32_e32 v28, v22, v56
	v_mul_f32_e32 v27, v23, v56
	v_mul_f32_e32 v26, v24, v56
	v_mul_f32_e32 v25, v25, v56
	v_mul_f32_e32 v24, v18, v56
	v_mul_f32_e32 v23, v19, v56
	v_mul_f32_e32 v22, v20, v56
	v_mul_f32_e32 v20, v21, v56
	s_cbranch_vccnz .LBB0_287
	v_mov_b32_e32 v18, v1
	v_mov_b32_e32 v19, v1
	v_cvt_scalef32_pk_fp4_f32 v18, v55, v54, 1.0
	v_cvt_scalef32_pk_fp4_f32 v19, v28, v27, 1.0
	v_cvt_scalef32_pk_fp4_f32 v18, v53, v33, 1.0 op_sel:[0,0,1,0]
	v_cvt_scalef32_pk_fp4_f32 v19, v26, v25, 1.0 op_sel:[0,0,1,0]
	v_cvt_scalef32_pk_fp4_f32 v18, v32, v31, 1.0 op_sel:[0,0,0,1]
	v_cvt_scalef32_pk_fp4_f32 v19, v24, v23, 1.0 op_sel:[0,0,0,1]
	v_cvt_scalef32_pk_fp4_f32 v18, v30, v29, 1.0 op_sel:[0,0,1,1]
	v_cvt_scalef32_pk_fp4_f32 v19, v22, v20, 1.0 op_sel:[0,0,1,1]
	s_mov_b32 s14, 0x3e2aaaab
	s_cbranch_execz .LBB0_288
